# hardening: the 16 K/V-projection workgroups write back their L2 right after their tile (K/V is consumed cross-group at steps 3/10 and no global barrier follows any more)
# speedup vs baseline: 1.0222x; 1.0052x over previous
.LBB0_173:
	s_waitcnt vmcnt(0)
	s_mov_b32 s76, s88
	s_mov_b64 s[64:65], s[90:91]
	s_barrier
	buffer_wbl2 sc1
	s_waitcnt vmcnt(0)
